# k23: k16 + code placement: one s_nop before the attention KV loop head and one before the K=4096 out-proj K-loop head so all hot loop heads sit at 8-byte phase 0 (attention and K4096 loop 64-B aligned
# speedup vs baseline: 1.0092x; 1.0092x over previous
; __device__ __forceinline__ int opaque_tid() { int t = threadIdx.x; asm volatile("" : "+v"(t)); return t; }
; __device__ __forceinline__ void attn_body(const bf16_t* Qb, const bf16_t* Kh, const bf16_t* Vh, const bf16_t* Gb, bf16_t* Ob, int seq, char* lds,
;                                           const float* qgain, const float* cosA, const float* sinA, int t0) {
;   const int tid = opaque_tid(), wid = tid >> 6, lane = tid & 63, r32 = lane & 31, hi = lane >> 5;
;   char* V_lds = lds; char* K_lds = lds + 2 * SHM_V;
;   float* ws = (float*)(lds + 2 * SHM_V + 2 * SHM_K) + wid * 64; float* li_l = ws; float* al_l = ws + 32;
;   float m_reg = -1e30f, l_reg = 0; f32x16 o[4] = {}; bf16x8 qr[8];
;   const bf16_t* Qw = Qb + (long)(wid * QBLK + r32) * LDQ + hi * 8;
; #pragma unroll
;   for (int d0 = 0; d0 < 8; ++d0) qr[d0] = ld8(Qw + d0 * 16);
;   {
;     float ss = 0.f;
; #pragma unroll
;     for (int d0 = 0; d0 < 8; ++d0)
; #pragma unroll
;       for (int e = 0; e < 8; ++e) { const float v = bf2f((unsigned short)qr[d0][e]); ss += v * v; }
;     { auto rr = __builtin_amdgcn_permlane32_swap(__float_as_uint(ss), __float_as_uint(ss), false, false); ss = __uint_as_float(rr[0]) + __uint_as_float(rr[1]); }
;     const float rinv = __builtin_amdgcn_rsqf(ss * (1.f / 128) + RMS_EPS);
;     const int t = t0 + wid * QBLK + r32, rp = t >> 6, cp = t & 63;
; #pragma unroll
;     for (int half = 0; half < 2; ++half) { const int pos = half ? cp : rp;
; #pragma unroll
;       for (int dd = 0; dd < 2; ++dd) { const int dx = 4 * half + dd, dy = dx + 2, i0 = 16 * dd + 8 * hi;
;         const f32x4 c0 = *(const f32x4*)(cosA + pos * 32 + i0), c1 = *(const f32x4*)(cosA + pos * 32 + i0 + 4), s0 = *(const f32x4*)(sinA + pos * 32 + i0), s1 = *(const f32x4*)(sinA + pos * 32 + i0 + 4);
;         const f32x4 gx0 = *(const f32x4*)(qgain + 16 * dx + 8 * hi), gx1 = *(const f32x4*)(qgain + 16 * dx + 8 * hi + 4), gy0 = *(const f32x4*)(qgain + 16 * dy + 8 * hi), gy1 = *(const f32x4*)(qgain + 16 * dy + 8 * hi + 4);
.LBB0_258:
	s_lshl_b32 s14, s46, 6
	s_and_b32 s20, s14, 0x300
	s_lshl_b32 s14, s48, 4
	s_and_b32 s38, s47, 0xfffff000
	s_and_b32 s15, s14, 0xfffff000
	s_ashr_i32 s39, s38, 31
	s_mul_i32 s16, s15, 0x2800
	s_mul_hi_i32 s14, s15, 0x2800
	s_add_u32 s19, s4, s16
	s_addc_u32 s21, s5, s14
	s_lshl_b32 s14, s48, 5
	s_and_b32 s17, s14, 0xf00
	s_mul_i32 s14, s17, 0x2800
	s_add_u32 s16, s19, s14
	s_addc_u32 s14, s21, 0
	s_lshl_b32 s18, s48, 8
	s_and_b32 s18, s18, 0x700
	s_and_b32 s22, s48, 0x80
	s_or_b32 s18, s18, s22
	s_lshl_b32 s22, s18, 1
	v_mov_b32_e32 v94, v252
	s_add_u32 s22, s16, s22
	s_addc_u32 s23, s14, 0
	v_ashrrev_i32_e32 v179, 6, v94
	v_and_b32_e32 v181, 31, v94
	v_lshlrev_b32_e32 v178, 5, v179
	v_bfe_u32 v184, v94, 5, 1
	v_or_b32_e32 v95, v178, v181
	v_mov_b64_e32 v[0:1], s[22:23]
	v_mad_i64_i32 v[0:1], s[22:23], v95, s72, v[0:1]
	v_lshlrev_b32_e32 v176, 4, v184
	v_lshl_add_u64 v[4:5], v[0:1], 0, v[176:177]
	s_waitcnt vmcnt(4)
	v_and_b32_e32 v38, 32, v94
	global_load_dwordx4 v[46:49], v[4:5], off offset:224
	global_load_dwordx4 v[54:57], v[4:5], off offset:160
	global_load_dwordx4 v[62:65], v[4:5], off offset:192
	global_load_dwordx4 v[66:69], v[4:5], off offset:128
	global_load_dwordx4 v[8:11], v38, s[40:41] offset:16
	global_load_dwordx4 v[0:3], v38, s[40:41] offset:144
	global_load_dwordx4 v[96:99], v[4:5], off offset:64
	global_load_dwordx4 v[80:83], v[4:5], off offset:96
	global_load_dwordx4 v[100:103], v[4:5], off
	global_load_dwordx4 v[104:107], v[4:5], off offset:32
	v_or_b32_e32 v6, s17, v181
	v_add_u32_e32 v6, v6, v178
	v_ashrrev_i32_e32 v6, 1, v6
	v_and_b32_e32 v6, 0xffffffe0, v6
	v_ashrrev_i32_e32 v7, 31, v6
	v_lshlrev_b64 v[4:5], 2, v[6:7]
	v_mov_b32_e32 v39, v177
	v_lshl_add_u64 v[6:7], s[98:99], 0, v[4:5]
	v_lshl_add_u64 v[4:5], s[24:25], 0, v[4:5]
	v_lshl_add_u64 v[72:73], v[4:5], 0, v[38:39]
	v_lshl_add_u64 v[70:71], v[6:7], 0, v[38:39]
	global_load_dwordx4 v[4:7], v[72:73], off offset:16
	global_load_dwordx4 v[12:15], v[70:71], off offset:16
	global_load_dwordx4 v[28:31], v38, s[40:41]
	global_load_dwordx4 v[24:27], v38, s[40:41] offset:128
	global_load_dwordx4 v[20:23], v[72:73], off
	global_load_dwordx4 v[16:19], v[70:71], off
	s_lshl_b32 s22, s48, 7
	s_and_b32 s22, s22, 0x300
	s_add_u32 s19, s19, s22
	s_addc_u32 s21, s21, 0
	s_add_u32 s36, s19, 0x1000
	s_addc_u32 s37, s21, 0
	s_add_u32 s42, s19, 0x1400
	s_addc_u32 s43, s21, 0
	v_lshlrev_b32_e32 v185, 4, v94
	v_and_b32_e32 v186, 63, v94
	s_add_i32 s19, 0, 0x10000
	s_cmp_lg_u32 0, -1
	s_cselect_b32 s21, 0, 0
	s_mov_b32 s72, s73
	s_mov_b32 s74, s73
	s_mov_b32 s75, s73
	s_mov_b32 s76, s73
	s_mov_b32 s77, s73
	s_mov_b32 s78, s73
	s_mov_b32 s79, s73
	s_mov_b32 s80, s73
	s_mov_b32 s81, s73
	s_mov_b32 s82, s73
	s_mov_b32 s83, s73
	s_mov_b32 s84, s73
	s_mov_b32 s85, s73
	s_mov_b32 s86, s73
	s_mov_b32 s87, s73
	v_mov_b32_e32 v189, 0
	s_waitcnt vmcnt(15)
	v_lshlrev_b32_e32 v35, 16, v49
	v_and_b32_e32 v33, 0xffff0000, v49
	v_lshlrev_b32_e32 v41, 16, v48
	s_waitcnt vmcnt(12)
	v_lshlrev_b32_e32 v52, 16, v69
	s_waitcnt vmcnt(9)
	v_and_b32_e32 v119, 0xffff0000, v97
	s_waitcnt vmcnt(7)
	v_lshlrev_b32_e32 v84, 16, v103
	v_and_b32_e32 v86, 0xffff0000, v103
	v_lshlrev_b32_e32 v103, 16, v97
	v_lshlrev_b32_e32 v121, 16, v96
	v_and_b32_e32 v97, 0xffff0000, v96
	v_and_b32_e32 v96, 0xffff0000, v100
	v_and_b32_e32 v50, 0xffff0000, v69
	v_lshlrev_b32_e32 v60, 16, v67
	v_and_b32_e32 v58, 0xffff0000, v67
	v_lshlrev_b32_e32 v69, 16, v83
	v_and_b32_e32 v67, 0xffff0000, v83
	v_lshlrev_b32_e32 v85, 16, v99
	v_mov_b32_e32 v91, v2
	v_and_b32_e32 v87, 0xffff0000, v99
	v_mov_b32_e32 v2, v11
	v_lshlrev_b32_e32 v75, 16, v82
	v_and_b32_e32 v11, 0xffff0000, v82
	v_lshlrev_b32_e32 v79, 16, v81
	s_waitcnt vmcnt(6)
	v_lshlrev_b32_e32 v78, 16, v105
	v_and_b32_e32 v77, 0xffff0000, v81
	v_and_b32_e32 v76, 0xffff0000, v105
	v_lshlrev_b32_e32 v83, 16, v80
	v_lshlrev_b32_e32 v82, 16, v104
	v_and_b32_e32 v81, 0xffff0000, v80
	v_and_b32_e32 v80, 0xffff0000, v104
	v_lshlrev_b32_e32 v105, 16, v98
	v_lshlrev_b32_e32 v104, 16, v102
	v_and_b32_e32 v99, 0xffff0000, v98
	v_and_b32_e32 v98, 0xffff0000, v102
	v_lshlrev_b32_e32 v102, 16, v101
	v_and_b32_e32 v118, 0xffff0000, v101
	v_lshlrev_b32_e32 v120, 16, v100
	v_pk_mul_f32 v[100:101], v[96:97], v[96:97]
	v_lshlrev_b32_e32 v74, 16, v106
	v_pk_fma_f32 v[124:125], v[120:121], v[120:121], v[100:101]
	v_mov_b32_e32 v90, v10
	v_pk_fma_f32 v[124:125], v[102:103], v[102:103], v[124:125]
	v_and_b32_e32 v10, 0xffff0000, v106
	v_pk_fma_f32 v[124:125], v[118:119], v[118:119], v[124:125]
	v_lshlrev_b32_e32 v40, 16, v56
	v_pk_fma_f32 v[124:125], v[104:105], v[104:105], v[124:125]
	v_and_b32_e32 v37, 0xffff0000, v48
	v_pk_fma_f32 v[124:125], v[98:99], v[98:99], v[124:125]
	v_and_b32_e32 v36, 0xffff0000, v56
	v_pk_fma_f32 v[124:125], v[84:85], v[84:85], v[124:125]
	v_lshlrev_b32_e32 v45, 16, v47
	v_pk_fma_f32 v[124:125], v[86:87], v[86:87], v[124:125]
	v_and_b32_e32 v43, 0xffff0000, v47
	v_pk_fma_f32 v[124:125], v[82:83], v[82:83], v[124:125]
	v_lshlrev_b32_e32 v49, 16, v46
	v_pk_fma_f32 v[124:125], v[80:81], v[80:81], v[124:125]
	v_lshlrev_b32_e32 v48, 16, v54
	v_pk_fma_f32 v[124:125], v[78:79], v[78:79], v[124:125]
	v_and_b32_e32 v47, 0xffff0000, v46
	v_pk_fma_f32 v[124:125], v[76:77], v[76:77], v[124:125]
	v_and_b32_e32 v46, 0xffff0000, v54
	v_pk_fma_f32 v[124:125], v[74:75], v[74:75], v[124:125]
	v_lshlrev_b32_e32 v56, 16, v68
	v_and_b32_e32 v54, 0xffff0000, v68
	v_lshlrev_b32_e32 v68, 16, v107
	v_pk_fma_f32 v[124:125], v[10:11], v[10:11], v[124:125]
	v_lshlrev_b32_e32 v34, 16, v57
	v_and_b32_e32 v32, 0xffff0000, v57
	v_lshlrev_b32_e32 v53, 16, v65
	v_and_b32_e32 v51, 0xffff0000, v65
; __device__ __forceinline__ void attn_body(const bf16_t* Qb, const bf16_t* Kh, const bf16_t* Vh, const bf16_t* Gb, bf16_t* Ob, int seq, char* lds,
;                                           const float* qgain, const float* cosA, const float* sinA, int t0) {
;     ...
;     float ss = 0.f;
; #pragma unroll
;     for (int d0 = 0; d0 < 8; ++d0)
; #pragma unroll
;       for (int e = 0; e < 8; ++e) { const float v = bf2f((unsigned short)qr[d0][e]); ss += v * v; }
;     { auto rr = __builtin_amdgcn_permlane32_swap(__float_as_uint(ss), __float_as_uint(ss), false, false); ss = __uint_as_float(rr[0]) + __uint_as_float(rr[1]); }
;     const float rinv = __builtin_amdgcn_rsqf(ss * (1.f / 128) + RMS_EPS);
;     const int t = t0 + wid * QBLK + r32, rp = t >> 6, cp = t & 63;
; #pragma unroll
;     for (int half = 0; half < 2; ++half) { const int pos = half ? cp : rp;
; #pragma unroll
;       for (int dd = 0; dd < 2; ++dd) { const int dx = 4 * half + dd, dy = dx + 2, i0 = 16 * dd + 8 * hi;
;         const f32x4 c0 = *(const f32x4*)(cosA + pos * 32 + i0), c1 = *(const f32x4*)(cosA + pos * 32 + i0 + 4), s0 = *(const f32x4*)(sinA + pos * 32 + i0), s1 = *(const f32x4*)(sinA + pos * 32 + i0 + 4);
;         const f32x4 gx0 = *(const f32x4*)(qgain + 16 * dx + 8 * hi), gx1 = *(const f32x4*)(qgain + 16 * dx + 8 * hi + 4), gy0 = *(const f32x4*)(qgain + 16 * dy + 8 * hi), gy1 = *(const f32x4*)(qgain + 16 * dy + 8 * hi + 4);
;         float xo[8], yo[8];
; #pragma unroll
;         for (int e = 0; e < 8; ++e) { const float cc = e < 4 ? c0[e & 3] : c1[e & 3], sn = e < 4 ? s0[e & 3] : s1[e & 3];
;           const float x = bf2f((unsigned short)qr[dx][e]) * rinv * (e < 4 ? gx0[e & 3] : gx1[e & 3]), y = bf2f((unsigned short)qr[dy][e]) * rinv * (e < 4 ? gy0[e & 3] : gy1[e & 3]);
;           xo[e] = x * cc - y * sn; yo[e] = y * cc + x * sn; }
	v_lshlrev_b32_e32 v44, 16, v55
	v_and_b32_e32 v42, 0xffff0000, v55
	v_lshlrev_b32_e32 v57, 16, v64
	v_and_b32_e32 v55, 0xffff0000, v64
	v_lshlrev_b32_e32 v61, 16, v63
	v_and_b32_e32 v59, 0xffff0000, v63
	v_lshlrev_b32_e32 v65, 16, v62
	v_lshlrev_b32_e32 v64, 16, v66
	v_and_b32_e32 v63, 0xffff0000, v62
	v_and_b32_e32 v62, 0xffff0000, v66
	v_and_b32_e32 v66, 0xffff0000, v107
	v_pk_fma_f32 v[124:125], v[68:69], v[68:69], v[124:125]
	v_mov_b32_e32 v107, v0
	v_pk_fma_f32 v[124:125], v[66:67], v[66:67], v[124:125]
	v_mul_f32_e32 v0, v121, v121
	v_pk_add_f32 v[124:125], v[0:1], v[124:125] op_sel_hi:[0,1]
	v_pk_add_f32 v[100:101], v[100:101], v[124:125] op_sel:[1,0] op_sel_hi:[0,1]
	v_mul_f32_e32 v0, v103, v103
	v_pk_add_f32 v[100:101], v[0:1], v[100:101] op_sel_hi:[0,1]
	v_mul_f32_e32 v0, v119, v119
	v_pk_add_f32 v[100:101], v[0:1], v[100:101] op_sel_hi:[0,1]
	v_mul_f32_e32 v0, v105, v105
	v_pk_add_f32 v[100:101], v[0:1], v[100:101] op_sel_hi:[0,1]
	v_mul_f32_e32 v0, v99, v99
	v_pk_add_f32 v[100:101], v[0:1], v[100:101] op_sel_hi:[0,1]
	v_mul_f32_e32 v0, v85, v85
	v_pk_add_f32 v[100:101], v[0:1], v[100:101] op_sel_hi:[0,1]
	v_mul_f32_e32 v0, v87, v87
	v_pk_add_f32 v[100:101], v[0:1], v[100:101] op_sel_hi:[0,1]
	v_mul_f32_e32 v0, v83, v83
	v_pk_add_f32 v[100:101], v[0:1], v[100:101] op_sel_hi:[0,1]
	v_mul_f32_e32 v0, v81, v81
	v_pk_add_f32 v[100:101], v[0:1], v[100:101] op_sel_hi:[0,1]
	v_mul_f32_e32 v0, v79, v79
	v_pk_add_f32 v[100:101], v[0:1], v[100:101] op_sel_hi:[0,1]
	v_mul_f32_e32 v0, v77, v77
	v_pk_add_f32 v[100:101], v[0:1], v[100:101] op_sel_hi:[0,1]
	v_mul_f32_e32 v0, v75, v75
	v_pk_add_f32 v[100:101], v[0:1], v[100:101] op_sel_hi:[0,1]
	v_mul_f32_e32 v0, v11, v11
	v_pk_add_f32 v[100:101], v[0:1], v[100:101] op_sel_hi:[0,1]
	v_mul_f32_e32 v0, v69, v69
	v_pk_add_f32 v[100:101], v[0:1], v[100:101] op_sel_hi:[0,1]
	v_mul_f32_e32 v0, v67, v67
	v_pk_add_f32 v[100:101], v[0:1], v[100:101] op_sel_hi:[0,1]
	v_pk_fma_f32 v[100:101], v[64:65], v[64:65], v[100:101]
	v_mul_f32_e32 v0, v65, v65
	v_pk_fma_f32 v[100:101], v[62:63], v[62:63], v[100:101]
	v_mov_b32_e32 v110, v37
	v_pk_fma_f32 v[100:101], v[60:61], v[60:61], v[100:101]
	v_mov_b32_e32 v111, v41
	v_pk_fma_f32 v[100:101], v[58:59], v[58:59], v[100:101]
	v_mov_b32_e32 v108, v33
	v_pk_fma_f32 v[100:101], v[56:57], v[56:57], v[100:101]
	v_mov_b32_e32 v109, v35
	v_pk_fma_f32 v[100:101], v[54:55], v[54:55], v[100:101]
	v_mov_b32_e32 v106, v8
	v_pk_fma_f32 v[100:101], v[52:53], v[52:53], v[100:101]
	s_waitcnt vmcnt(2)
	v_mov_b32_e32 v123, v24
	v_pk_fma_f32 v[100:101], v[50:51], v[50:51], v[100:101]
	v_mov_b32_e32 v24, v29
	v_pk_fma_f32 v[100:101], v[48:49], v[48:49], v[100:101]
	v_mov_b32_e32 v114, v30
	v_pk_fma_f32 v[100:101], v[46:47], v[46:47], v[100:101]
	v_mov_b32_e32 v115, v26
	v_pk_fma_f32 v[100:101], v[44:45], v[44:45], v[100:101]
	v_mov_b32_e32 v122, v28
	v_pk_fma_f32 v[100:101], v[42:43], v[42:43], v[100:101]
	s_waitcnt vmcnt(1)
	v_mov_b32_e32 v116, v22
	v_pk_fma_f32 v[100:101], v[40:41], v[40:41], v[100:101]
	s_waitcnt vmcnt(0)
	v_mov_b32_e32 v117, v18
	v_pk_fma_f32 v[100:101], v[36:37], v[36:37], v[100:101]
	v_mov_b32_e32 v26, v31
	v_pk_fma_f32 v[100:101], v[34:35], v[34:35], v[100:101]
	v_mov_b32_e32 v112, v4
	v_pk_fma_f32 v[100:101], v[32:33], v[32:33], v[100:101]
	v_mov_b32_e32 v113, v12
	v_pk_add_f32 v[100:101], v[0:1], v[100:101] op_sel_hi:[0,1]
	v_mul_f32_e32 v0, v63, v63
	v_pk_add_f32 v[100:101], v[0:1], v[100:101] op_sel_hi:[0,1]
	v_mul_f32_e32 v0, v61, v61
	v_pk_add_f32 v[100:101], v[0:1], v[100:101] op_sel_hi:[0,1]
	v_mul_f32_e32 v0, v59, v59
	v_pk_add_f32 v[100:101], v[0:1], v[100:101] op_sel_hi:[0,1]
	v_mul_f32_e32 v0, v57, v57
	v_pk_add_f32 v[100:101], v[0:1], v[100:101] op_sel_hi:[0,1]
	v_mul_f32_e32 v0, v55, v55
	v_pk_add_f32 v[100:101], v[0:1], v[100:101] op_sel_hi:[0,1]
	v_mul_f32_e32 v0, v53, v53
	v_pk_add_f32 v[100:101], v[0:1], v[100:101] op_sel_hi:[0,1]
	v_mul_f32_e32 v0, v51, v51
	v_pk_add_f32 v[100:101], v[0:1], v[100:101] op_sel_hi:[0,1]
	v_mul_f32_e32 v0, v49, v49
	v_pk_add_f32 v[100:101], v[0:1], v[100:101] op_sel_hi:[0,1]
	v_mul_f32_e32 v0, v47, v47
	v_pk_add_f32 v[100:101], v[0:1], v[100:101] op_sel_hi:[0,1]
	v_mul_f32_e32 v0, v45, v45
	v_pk_add_f32 v[100:101], v[0:1], v[100:101] op_sel_hi:[0,1]
	v_mul_f32_e32 v0, v43, v43
	v_pk_add_f32 v[100:101], v[0:1], v[100:101] op_sel_hi:[0,1]
	v_mul_f32_e32 v0, v41, v41
	v_pk_add_f32 v[100:101], v[0:1], v[100:101] op_sel_hi:[0,1]
	v_pk_fma_f32 v[100:101], v[110:111], v[110:111], v[100:101]
	v_mul_f32_e32 v0, v35, v35
	v_pk_add_f32 v[100:101], v[0:1], v[100:101] op_sel_hi:[0,1]
	v_pk_fma_f32 v[100:101], v[108:109], v[108:109], v[100:101]
	v_mov_b32_e32 v110, v16
	v_mov_b32_e32 v0, v100
	s_nop 1
	v_permlane32_swap_b32_e32 v100, v0
	v_add_f32_e32 v0, v100, v0
	v_fmamk_f32 v0, v0, 0x3c000000, v244
	v_rsq_f32_e32 v8, v0
	v_mov_b32_e32 v101, v16
	v_mov_b32_e32 v16, v21
	v_mov_b32_e32 v100, v20
	v_pk_mul_f32 v[96:97], v[8:9], v[96:97] op_sel_hi:[0,1]
	v_pk_mul_f32 v[24:25], v[24:25], v[96:97]
	v_mov_b32_e32 v111, v20
	v_mov_b32_e32 v20, v17
	v_pk_mul_f32 v[16:17], v[16:17], v[24:25]
	v_pk_mul_f32 v[28:29], v[20:21], v[24:25]
	v_add_f32_e32 v24, v16, v17
	v_pk_mul_f32 v[16:17], v[8:9], v[102:103] op_sel_hi:[0,1]
	v_pk_mul_f32 v[16:17], v[114:115], v[16:17]
	v_mov_b32_e32 v20, v18
	v_mov_b32_e32 v21, v22
	v_pk_mul_f32 v[20:21], v[20:21], v[16:17]
	v_pk_mul_f32 v[16:17], v[116:117], v[16:17]
	v_sub_f32_e32 v28, v28, v29
	v_add_f32_e32 v29, v16, v17
	v_pk_mul_f32 v[16:17], v[8:9], v[118:119] op_sel_hi:[0,1]
	v_pk_mul_f32 v[16:17], v[26:27], v[16:17]
	v_mov_b32_e32 v22, v19
	v_mov_b32_e32 v18, v23
	v_sub_f32_e32 v25, v20, v21
; __device__ __forceinline__ unsigned cvtpk(float lo, float hi) { unsigned r; asm volatile("v_cvt_pk_bf16_f32 %0, %1, %2" : "=v"(r) : "v"(lo), "v"(hi)); return r; }
; __device__ __forceinline__ unsigned cvtpk(float lo, float hi) { unsigned r; asm volatile("v_cvt_pk_bf16_f32 %0, %1, %2" : "=v"(r) : "v"(lo), "v"(hi)); return r; }
; __device__ __forceinline__ void attn_body(const bf16_t* Qb, const bf16_t* Kh, const bf16_t* Vh, const bf16_t* Gb, bf16_t* Ob, int seq, char* lds,
;                                           const float* qgain, const float* cosA, const float* sinA, int t0) {
;     ...
;     for (int half = 0; half < 2; ++half) { const int pos = half ? cp : rp;
; #pragma unroll
;       for (int dd = 0; dd < 2; ++dd) { const int dx = 4 * half + dd, dy = dx + 2, i0 = 16 * dd + 8 * hi;
;         const f32x4 c0 = *(const f32x4*)(cosA + pos * 32 + i0), c1 = *(const f32x4*)(cosA + pos * 32 + i0 + 4), s0 = *(const f32x4*)(sinA + pos * 32 + i0), s1 = *(const f32x4*)(sinA + pos * 32 + i0 + 4);
;         const f32x4 gx0 = *(const f32x4*)(qgain + 16 * dx + 8 * hi), gx1 = *(const f32x4*)(qgain + 16 * dx + 8 * hi + 4), gy0 = *(const f32x4*)(qgain + 16 * dy + 8 * hi), gy1 = *(const f32x4*)(qgain + 16 * dy + 8 * hi + 4);
;         float xo[8], yo[8];
; #pragma unroll
;         for (int e = 0; e < 8; ++e) { const float cc = e < 4 ? c0[e & 3] : c1[e & 3], sn = e < 4 ? s0[e & 3] : s1[e & 3];
;           const float x = bf2f((unsigned short)qr[dx][e]) * rinv * (e < 4 ? gx0[e & 3] : gx1[e & 3]), y = bf2f((unsigned short)qr[dy][e]) * rinv * (e < 4 ? gy0[e & 3] : gy1[e & 3]);
;           xo[e] = x * cc - y * sn; yo[e] = y * cc + x * sn; }
;         u32x4 wx = {cvtpk(xo[0], xo[1]), cvtpk(xo[2], xo[3]), cvtpk(xo[4], xo[5]), cvtpk(xo[6], xo[7])}, wy = {cvtpk(yo[0], yo[1]), cvtpk(yo[2], yo[3]), cvtpk(yo[4], yo[5]), cvtpk(yo[6], yo[7])};
;         qr[dx] = *reinterpret_cast<bf16x8*>(&wx); qr[dy] = *reinterpret_cast<bf16x8*>(&wy); } }
	v_pk_mul_f32 v[20:21], v[22:23], v[16:17]
	v_pk_mul_f32 v[16:17], v[18:19], v[16:17]
	v_sub_f32_e32 v20, v20, v21
	v_add_f32_e32 v21, v16, v17
	v_pk_mul_f32 v[16:17], v[8:9], v[104:105] op_sel_hi:[0,1]
	v_pk_mul_f32 v[16:17], v[16:17], v[106:107]
	v_mov_b32_e32 v18, v12
	v_mov_b32_e32 v19, v4
	v_pk_mul_f32 v[18:19], v[18:19], v[16:17]
	v_pk_mul_f32 v[16:17], v[112:113], v[16:17]
	v_sub_f32_e32 v18, v18, v19
	v_add_f32_e32 v19, v16, v17
	v_pk_mul_f32 v[16:17], v[8:9], v[98:99] op_sel_hi:[0,1]
	v_mov_b32_e32 v0, v9
	v_pk_mul_f32 v[0:1], v[16:17], v[0:1]
	v_mov_b32_e32 v4, v13
	v_pk_mul_f32 v[16:17], v[4:5], v[0:1]
	v_mov_b32_e32 v12, v5
	v_pk_mul_f32 v[108:109], v[8:9], v[120:121] op_sel_hi:[0,1]
	v_sub_f32_e32 v9, v16, v17
	v_pk_mul_f32 v[0:1], v[12:13], v[0:1]
	v_mov_b32_e32 v88, v6
	v_add_f32_e32 v12, v0, v1
	v_pk_mul_f32 v[0:1], v[8:9], v[84:85] op_sel_hi:[0,1]
	v_mov_b32_e32 v89, v14
	v_pk_mul_f32 v[0:1], v[0:1], v[90:91]
	v_mov_b32_e32 v4, v14
	v_mov_b32_e32 v5, v6
	v_pk_mul_f32 v[4:5], v[4:5], v[0:1]
	v_pk_mul_f32 v[0:1], v[88:89], v[0:1]
	v_sub_f32_e32 v4, v4, v5
	v_add_f32_e32 v5, v0, v1
	v_pk_mul_f32 v[0:1], v[8:9], v[86:87] op_sel_hi:[0,1]
	v_pk_mul_f32 v[108:109], v[122:123], v[108:109]
	v_pk_mul_f32 v[0:1], v[0:1], v[2:3]
	v_mov_b32_e32 v6, v15
	v_mov_b32_e32 v92, v7
	v_mov_b32_e32 v93, v15
	v_pk_mul_f32 v[110:111], v[110:111], v[108:109]
	v_pk_mul_f32 v[2:3], v[6:7], v[0:1]
	v_sub_f32_e32 v30, v110, v111
	v_pk_mul_f32 v[100:101], v[100:101], v[108:109]
	v_sub_f32_e32 v2, v2, v3
	v_pk_mul_f32 v[0:1], v[92:93], v[0:1]
	v_add_f32_e32 v108, v100, v101
	v_add_f32_e32 v0, v0, v1
	v_cvt_pk_bf16_f32 v100, v30, v28
	v_cvt_pk_bf16_f32 v101, v25, v20
	v_cvt_pk_bf16_f32 v102, v18, v9
	v_cvt_pk_bf16_f32 v103, v4, v2
	v_cvt_pk_bf16_f32 v96, v108, v24
	v_cvt_pk_bf16_f32 v97, v29, v21
	v_cvt_pk_bf16_f32 v98, v19, v12
	v_cvt_pk_bf16_f32 v99, v5, v0
	global_load_dwordx4 v[2:5], v38, s[40:41] offset:64
	global_load_dwordx4 v[12:15], v38, s[40:41] offset:192
	global_load_dwordx4 v[16:19], v[70:71], off offset:64
	global_load_dwordx4 v[20:23], v[72:73], off offset:64
	global_load_dwordx4 v[24:27], v38, s[40:41] offset:80
	global_load_dwordx4 v[28:31], v38, s[40:41] offset:208
	global_load_dwordx4 v[84:87], v[70:71], off offset:80
	s_nop 0
	global_load_dwordx4 v[70:73], v[72:73], off offset:80
	v_lshlrev_b32_e32 v0, 7, v95
	v_and_b32_e32 v0, 0x1f80, v0
	v_mov_b32_e32 v1, v177
	v_lshl_add_u64 v[6:7], s[98:99], 0, v[0:1]
	v_lshl_add_u64 v[88:89], s[24:25], 0, v[0:1]
	v_lshl_add_u64 v[0:1], v[6:7], 0, v[38:39]
	v_pk_mul_f32 v[6:7], v[8:9], v[82:83] op_sel_hi:[0,1]
	s_waitcnt vmcnt(7)
	v_mov_b32_e32 v82, v2
	s_waitcnt vmcnt(6)
	v_mov_b32_e32 v83, v12
	v_pk_mul_f32 v[6:7], v[6:7], v[82:83]
	s_waitcnt vmcnt(5)
	v_mov_b32_e32 v82, v16
	s_waitcnt vmcnt(4)
	v_mov_b32_e32 v83, v20
	v_pk_mul_f32 v[82:83], v[82:83], v[6:7]
	v_mov_b32_e32 v12, v3
	v_sub_f32_e32 v9, v82, v83
	v_mov_b32_e32 v82, v20
	v_mov_b32_e32 v83, v16
	v_pk_mul_f32 v[6:7], v[82:83], v[6:7]
	v_mov_b32_e32 v20, v17
	v_add_f32_e32 v82, v6, v7
	v_pk_mul_f32 v[6:7], v[8:9], v[80:81] op_sel_hi:[0,1]
	v_pk_mul_f32 v[2:3], v[6:7], v[12:13]
	v_mov_b32_e32 v16, v21
	v_pk_mul_f32 v[6:7], v[20:21], v[2:3]
	v_pk_mul_f32 v[2:3], v[16:17], v[2:3]
	v_sub_f32_e32 v12, v6, v7
	v_add_f32_e32 v13, v2, v3
	v_pk_mul_f32 v[2:3], v[8:9], v[78:79] op_sel_hi:[0,1]
	v_mov_b32_e32 v6, v4
	v_mov_b32_e32 v7, v14
	v_pk_mul_f32 v[2:3], v[2:3], v[6:7]
	v_mov_b32_e32 v6, v18
	v_mov_b32_e32 v7, v22
	v_pk_mul_f32 v[6:7], v[6:7], v[2:3]
	v_mov_b32_e32 v14, v5
	v_sub_f32_e32 v16, v6, v7
	v_mov_b32_e32 v6, v22
	v_mov_b32_e32 v7, v18
	v_pk_mul_f32 v[2:3], v[6:7], v[2:3]
	v_mov_b32_e32 v22, v19
	v_add_f32_e32 v6, v2, v3
	v_pk_mul_f32 v[2:3], v[8:9], v[76:77] op_sel_hi:[0,1]
	v_pk_mul_f32 v[2:3], v[2:3], v[14:15]
	v_mov_b32_e32 v18, v23
	v_pk_mul_f32 v[4:5], v[22:23], v[2:3]
	v_pk_mul_f32 v[2:3], v[18:19], v[2:3]
	v_sub_f32_e32 v7, v4, v5
	v_add_f32_e32 v14, v2, v3
	v_pk_mul_f32 v[2:3], v[8:9], v[74:75] op_sel_hi:[0,1]
	s_waitcnt vmcnt(3)
	v_mov_b32_e32 v4, v24
	s_waitcnt vmcnt(2)
	v_mov_b32_e32 v5, v28
	v_pk_mul_f32 v[2:3], v[2:3], v[4:5]
	s_waitcnt vmcnt(1)
	v_mov_b32_e32 v4, v84
	s_waitcnt vmcnt(0)
	v_mov_b32_e32 v5, v70
	v_pk_mul_f32 v[4:5], v[4:5], v[2:3]
	v_mov_b32_e32 v28, v25
	v_sub_f32_e32 v15, v4, v5
	v_mov_b32_e32 v4, v70
	v_mov_b32_e32 v5, v84
	v_pk_mul_f32 v[2:3], v[4:5], v[2:3]
	v_mov_b32_e32 v70, v85
	v_add_f32_e32 v17, v2, v3
	v_pk_mul_f32 v[2:3], v[8:9], v[10:11] op_sel_hi:[0,1]
	v_pk_mul_f32 v[2:3], v[2:3], v[28:29]
	v_mov_b32_e32 v84, v71
	v_pk_mul_f32 v[4:5], v[70:71], v[2:3]
	v_pk_mul_f32 v[2:3], v[84:85], v[2:3]
	v_sub_f32_e32 v10, v4, v5
	v_add_f32_e32 v11, v2, v3
	v_pk_mul_f32 v[2:3], v[8:9], v[68:69] op_sel_hi:[0,1]
	v_mov_b32_e32 v4, v26
	v_mov_b32_e32 v5, v30
	v_pk_mul_f32 v[2:3], v[2:3], v[4:5]
	v_mov_b32_e32 v4, v86
	v_mov_b32_e32 v5, v72
	v_pk_mul_f32 v[4:5], v[4:5], v[2:3]
	v_mov_b32_e32 v30, v27
	v_sub_f32_e32 v18, v4, v5
	v_mov_b32_e32 v4, v72
	v_mov_b32_e32 v5, v86
	v_pk_mul_f32 v[2:3], v[4:5], v[2:3]
	v_mov_b32_e32 v72, v87
	v_add_f32_e32 v19, v2, v3
	v_pk_mul_f32 v[2:3], v[8:9], v[66:67] op_sel_hi:[0,1]
	v_pk_mul_f32 v[2:3], v[2:3], v[30:31]
	v_mov_b32_e32 v86, v73
	v_pk_mul_f32 v[4:5], v[72:73], v[2:3]
	v_pk_mul_f32 v[2:3], v[86:87], v[2:3]
	v_sub_f32_e32 v4, v4, v5
	v_add_f32_e32 v2, v2, v3
	v_cvt_pk_bf16_f32 v108, v9, v12
	v_cvt_pk_bf16_f32 v109, v16, v7
	v_cvt_pk_bf16_f32 v110, v15, v10
	v_cvt_pk_bf16_f32 v111, v18, v4
	v_cvt_pk_bf16_f32 v104, v82, v13
	v_cvt_pk_bf16_f32 v105, v6, v14
	v_cvt_pk_bf16_f32 v106, v17, v11
	v_cvt_pk_bf16_f32 v107, v19, v2
	global_load_dwordx4 v[2:5], v38, s[40:41] offset:256
	global_load_dwordx4 v[10:13], v38, s[40:41] offset:384
	v_lshl_add_u64 v[6:7], v[88:89], 0, v[38:39]
	global_load_dwordx4 v[14:17], v[0:1], off
	global_load_dwordx4 v[18:21], v[6:7], off
	global_load_dwordx4 v[22:25], v38, s[40:41] offset:272
	global_load_dwordx4 v[26:29], v38, s[40:41] offset:400
	global_load_dwordx4 v[66:69], v[0:1], off offset:16
	global_load_dwordx4 v[70:73], v[6:7], off offset:16
	v_pk_mul_f32 v[30:31], v[8:9], v[64:65] op_sel_hi:[0,1]
	s_waitcnt vmcnt(7)
; __device__ __forceinline__ unsigned cvtpk(float lo, float hi) { unsigned r; asm volatile("v_cvt_pk_bf16_f32 %0, %1, %2" : "=v"(r) : "v"(lo), "v"(hi)); return r; }
; __device__ __forceinline__ int v_st(int k, int c) { const int kk = (k & ~0xC) | ((k & 4) << 1) | ((k & 8) >> 1); return ((kk >> 3) * 4 + (c >> 5)) * 512 + ((kk & 7) * 32 + (c & 31)) * 2; }
; __device__ __forceinline__ int v_rd_base(int lane) { return ((lane & 3) << 3) | (((lane >> 2) & 3) << 6) | (((lane >> 4) & 1) << 5) | (((lane >> 5) & 1) << 8); }
; __device__ __forceinline__ void attn_body(const bf16_t* Qb, const bf16_t* Kh, const bf16_t* Vh, const bf16_t* Gb, bf16_t* Ob, int seq, char* lds,
;                                           const float* qgain, const float* cosA, const float* sinA, int t0) {
;     ...
;     for (int half = 0; half < 2; ++half) { const int pos = half ? cp : rp;
; #pragma unroll
;       for (int dd = 0; dd < 2; ++dd) { const int dx = 4 * half + dd, dy = dx + 2, i0 = 16 * dd + 8 * hi;
;         const f32x4 c0 = *(const f32x4*)(cosA + pos * 32 + i0), c1 = *(const f32x4*)(cosA + pos * 32 + i0 + 4), s0 = *(const f32x4*)(sinA + pos * 32 + i0), s1 = *(const f32x4*)(sinA + pos * 32 + i0 + 4);
;         const f32x4 gx0 = *(const f32x4*)(qgain + 16 * dx + 8 * hi), gx1 = *(const f32x4*)(qgain + 16 * dx + 8 * hi + 4), gy0 = *(const f32x4*)(qgain + 16 * dy + 8 * hi), gy1 = *(const f32x4*)(qgain + 16 * dy + 8 * hi + 4);
;         float xo[8], yo[8];
; #pragma unroll
;         for (int e = 0; e < 8; ++e) { const float cc = e < 4 ? c0[e & 3] : c1[e & 3], sn = e < 4 ? s0[e & 3] : s1[e & 3];
;           const float x = bf2f((unsigned short)qr[dx][e]) * rinv * (e < 4 ? gx0[e & 3] : gx1[e & 3]), y = bf2f((unsigned short)qr[dy][e]) * rinv * (e < 4 ? gy0[e & 3] : gy1[e & 3]);
;           xo[e] = x * cc - y * sn; yo[e] = y * cc + x * sn; }
;         u32x4 wx = {cvtpk(xo[0], xo[1]), cvtpk(xo[2], xo[3]), cvtpk(xo[4], xo[5]), cvtpk(xo[6], xo[7])}, wy = {cvtpk(yo[0], yo[1]), cvtpk(yo[2], yo[3]), cvtpk(yo[4], yo[5]), cvtpk(yo[6], yo[7])};
;         qr[dx] = *reinterpret_cast<bf16x8*>(&wx); qr[dy] = *reinterpret_cast<bf16x8*>(&wy); } }
;   }
;   const int sr = tid >> 4, sc = (tid & 15) * 8, vst0 = v_st(sr, sc), vst1 = v_st(32 + sr, sc);
;   const int vb0 = (int)(uintptr_t)V_lds + v_rd_base(lane);
	v_mov_b32_e32 v64, v2
	s_waitcnt vmcnt(6)
	v_mov_b32_e32 v65, v10
	v_pk_mul_f32 v[30:31], v[30:31], v[64:65]
	s_waitcnt vmcnt(5)
	v_mov_b32_e32 v64, v14
	s_waitcnt vmcnt(4)
	v_mov_b32_e32 v65, v18
	v_pk_mul_f32 v[64:65], v[64:65], v[30:31]
	v_mov_b32_e32 v10, v3
	v_sub_f32_e32 v9, v64, v65
	v_mov_b32_e32 v64, v18
	v_mov_b32_e32 v65, v14
	v_pk_mul_f32 v[30:31], v[64:65], v[30:31]
	v_mov_b32_e32 v18, v15
	v_add_f32_e32 v39, v30, v31
	v_pk_mul_f32 v[30:31], v[8:9], v[62:63] op_sel_hi:[0,1]
	v_pk_mul_f32 v[2:3], v[30:31], v[10:11]
	v_mov_b32_e32 v14, v19
	v_pk_mul_f32 v[10:11], v[18:19], v[2:3]
	v_pk_mul_f32 v[2:3], v[14:15], v[2:3]
	v_sub_f32_e32 v18, v10, v11
	v_add_f32_e32 v14, v2, v3
	v_pk_mul_f32 v[2:3], v[8:9], v[60:61] op_sel_hi:[0,1]
	v_mov_b32_e32 v10, v4
	v_mov_b32_e32 v11, v12
	v_pk_mul_f32 v[2:3], v[2:3], v[10:11]
	v_mov_b32_e32 v10, v16
	v_mov_b32_e32 v11, v20
	v_pk_mul_f32 v[10:11], v[10:11], v[2:3]
	v_mov_b32_e32 v12, v5
	v_sub_f32_e32 v15, v10, v11
	v_mov_b32_e32 v10, v20
	v_mov_b32_e32 v11, v16
	v_pk_mul_f32 v[2:3], v[10:11], v[2:3]
	v_mov_b32_e32 v20, v17
	v_add_f32_e32 v10, v2, v3
	v_pk_mul_f32 v[2:3], v[8:9], v[58:59] op_sel_hi:[0,1]
	v_pk_mul_f32 v[2:3], v[2:3], v[12:13]
	v_mov_b32_e32 v16, v21
	v_pk_mul_f32 v[4:5], v[20:21], v[2:3]
	v_pk_mul_f32 v[2:3], v[16:17], v[2:3]
	v_sub_f32_e32 v11, v4, v5
	v_add_f32_e32 v12, v2, v3
	v_pk_mul_f32 v[2:3], v[8:9], v[56:57] op_sel_hi:[0,1]
	s_waitcnt vmcnt(3)
	v_mov_b32_e32 v4, v22
	s_waitcnt vmcnt(2)
	v_mov_b32_e32 v5, v26
	v_pk_mul_f32 v[2:3], v[2:3], v[4:5]
	s_waitcnt vmcnt(1)
	v_mov_b32_e32 v4, v66
	s_waitcnt vmcnt(0)
	v_mov_b32_e32 v5, v70
	v_pk_mul_f32 v[4:5], v[4:5], v[2:3]
	v_mov_b32_e32 v26, v23
	v_sub_f32_e32 v13, v4, v5
	v_mov_b32_e32 v4, v70
	v_mov_b32_e32 v5, v66
	v_pk_mul_f32 v[2:3], v[4:5], v[2:3]
	v_mov_b32_e32 v70, v67
	v_add_f32_e32 v16, v2, v3
	v_pk_mul_f32 v[2:3], v[8:9], v[54:55] op_sel_hi:[0,1]
	v_pk_mul_f32 v[2:3], v[2:3], v[26:27]
	v_mov_b32_e32 v66, v71
	v_pk_mul_f32 v[4:5], v[70:71], v[2:3]
	v_pk_mul_f32 v[2:3], v[66:67], v[2:3]
	v_sub_f32_e32 v17, v4, v5
	v_add_f32_e32 v19, v2, v3
	v_pk_mul_f32 v[2:3], v[8:9], v[52:53] op_sel_hi:[0,1]
	v_mov_b32_e32 v4, v24
	v_mov_b32_e32 v5, v28
	v_pk_mul_f32 v[2:3], v[2:3], v[4:5]
	v_mov_b32_e32 v4, v68
	v_mov_b32_e32 v5, v72
	v_pk_mul_f32 v[4:5], v[4:5], v[2:3]
	v_mov_b32_e32 v28, v25
	v_sub_f32_e32 v20, v4, v5
	v_mov_b32_e32 v4, v72
	v_mov_b32_e32 v5, v68
	v_pk_mul_f32 v[2:3], v[4:5], v[2:3]
	v_mov_b32_e32 v72, v69
	v_add_f32_e32 v21, v2, v3
	v_pk_mul_f32 v[2:3], v[8:9], v[50:51] op_sel_hi:[0,1]
	v_pk_mul_f32 v[2:3], v[2:3], v[28:29]
	v_mov_b32_e32 v68, v73
	v_pk_mul_f32 v[4:5], v[72:73], v[2:3]
	v_pk_mul_f32 v[2:3], v[68:69], v[2:3]
	v_sub_f32_e32 v4, v4, v5
	v_add_f32_e32 v2, v2, v3
	v_cvt_pk_bf16_f32 v116, v9, v18
	v_cvt_pk_bf16_f32 v117, v15, v11
	v_cvt_pk_bf16_f32 v118, v13, v17
	v_cvt_pk_bf16_f32 v119, v20, v4
	v_cvt_pk_bf16_f32 v112, v39, v14
	v_cvt_pk_bf16_f32 v113, v10, v12
	v_cvt_pk_bf16_f32 v114, v16, v19
	v_cvt_pk_bf16_f32 v115, v21, v2
	global_load_dwordx4 v[2:5], v38, s[40:41] offset:320
	global_load_dwordx4 v[10:13], v38, s[40:41] offset:448
	global_load_dwordx4 v[14:17], v[0:1], off offset:64
	global_load_dwordx4 v[18:21], v[6:7], off offset:64
	global_load_dwordx4 v[22:25], v38, s[40:41] offset:336
	global_load_dwordx4 v[26:29], v38, s[40:41] offset:464
	global_load_dwordx4 v[50:53], v[0:1], off offset:80
	global_load_dwordx4 v[54:57], v[6:7], off offset:80
	v_pk_mul_f32 v[0:1], v[8:9], v[48:49] op_sel_hi:[0,1]
	v_ashrrev_i32_e32 v48, 4, v94
	v_add_u32_e32 v66, 0x80, v48
	v_mad_i64_i32 v[66:67], s[22:23], v66, s69, 0
	v_add_u32_e32 v70, 0xa0, v48
	v_mad_i64_i32 v[70:71], s[22:23], v70, s69, 0
	v_ashrrev_i32_e32 v49, 31, v48
	s_waitcnt vmcnt(7)
	v_mov_b32_e32 v6, v2
	s_waitcnt vmcnt(6)
	v_mov_b32_e32 v7, v10
	v_pk_mul_f32 v[0:1], v[0:1], v[6:7]
	s_waitcnt vmcnt(5)
	v_mov_b32_e32 v6, v14
	s_waitcnt vmcnt(4)
	v_mov_b32_e32 v7, v18
	v_pk_mul_f32 v[6:7], v[6:7], v[0:1]
	v_mov_b32_e32 v10, v3
	v_sub_f32_e32 v9, v6, v7
	v_mov_b32_e32 v6, v18
	v_mov_b32_e32 v7, v14
	v_pk_mul_f32 v[0:1], v[6:7], v[0:1]
	v_mov_b32_e32 v18, v15
	v_add_f32_e32 v6, v0, v1
	v_pk_mul_f32 v[0:1], v[8:9], v[46:47] op_sel_hi:[0,1]
	v_pk_mul_f32 v[0:1], v[0:1], v[10:11]
	v_mov_b32_e32 v14, v19
	v_pk_mul_f32 v[2:3], v[18:19], v[0:1]
	v_pk_mul_f32 v[0:1], v[14:15], v[0:1]
	v_sub_f32_e32 v7, v2, v3
	v_add_f32_e32 v10, v0, v1
	v_pk_mul_f32 v[0:1], v[8:9], v[44:45] op_sel_hi:[0,1]
	v_mov_b32_e32 v2, v4
	v_mov_b32_e32 v3, v12
	v_pk_mul_f32 v[0:1], v[0:1], v[2:3]
	v_mov_b32_e32 v2, v16
	v_mov_b32_e32 v3, v20
	v_pk_mul_f32 v[2:3], v[2:3], v[0:1]
	v_mov_b32_e32 v12, v5
	v_sub_f32_e32 v4, v2, v3
	v_mov_b32_e32 v2, v20
	v_mov_b32_e32 v3, v16
	v_pk_mul_f32 v[0:1], v[2:3], v[0:1]
	v_mov_b32_e32 v20, v17
	v_add_f32_e32 v11, v0, v1
	v_pk_mul_f32 v[0:1], v[8:9], v[42:43] op_sel_hi:[0,1]
	v_pk_mul_f32 v[0:1], v[0:1], v[12:13]
	v_mov_b32_e32 v16, v21
	v_pk_mul_f32 v[2:3], v[20:21], v[0:1]
	v_pk_mul_f32 v[0:1], v[16:17], v[0:1]
	v_sub_f32_e32 v5, v2, v3
	v_add_f32_e32 v12, v0, v1
	v_pk_mul_f32 v[0:1], v[8:9], v[40:41] op_sel_hi:[0,1]
	s_waitcnt vmcnt(3)
	v_mov_b32_e32 v2, v22
	s_waitcnt vmcnt(2)
	v_mov_b32_e32 v3, v26
	v_pk_mul_f32 v[0:1], v[0:1], v[2:3]
	s_waitcnt vmcnt(1)
	v_mov_b32_e32 v2, v50
	s_waitcnt vmcnt(0)
; __device__ __forceinline__ unsigned cvtpk(float lo, float hi) { unsigned r; asm volatile("v_cvt_pk_bf16_f32 %0, %1, %2" : "=v"(r) : "v"(lo), "v"(hi)); return r; }
; __device__ __forceinline__ int v_st(int k, int c) { const int kk = (k & ~0xC) | ((k & 4) << 1) | ((k & 8) >> 1); return ((kk >> 3) * 4 + (c >> 5)) * 512 + ((kk & 7) * 32 + (c & 31)) * 2; }
; __device__ __forceinline__ int v_rd_base(int lane) { return ((lane & 3) << 3) | (((lane >> 2) & 3) << 6) | (((lane >> 4) & 1) << 5) | (((lane >> 5) & 1) << 8); }
; #define SLOAD(i, k0) do { sr_[i].vs0 = ld8(&Vh[(long)((k0) + sr) * LDK + sc]); sr_[i].vs1 = ld8(&Vh[(long)((k0) + 32 + sr) * LDK + sc]); \
;     sr_[i].ks0 = ld8(&Kh[(long)((k0) + sr) * LDK + sc]); sr_[i].ks1 = ld8(&Kh[(long)((k0) + 32 + sr) * LDK + sc]); } while (0)
; #define SWRITE(b, i) do { *(bf16x8*)(V_lds + (b) * SHM_V + vst0) = sr_[i].vs0;          \
;     *(bf16x8*)(V_lds + (b) * SHM_V + vst1) = sr_[i].vs1; int kc = sc * 2;               \
;     *(bf16x8*)(K_lds + (b) * SHM_K + KSWZ(sr, kc)) = sr_[i].ks0;                       \
;     *(bf16x8*)(K_lds + (b) * SHM_K + KSWZ(32 + sr, kc)) = sr_[i].ks1; } while (0)
; __device__ __forceinline__ void attn_body(const bf16_t* Qb, const bf16_t* Kh, const bf16_t* Vh, const bf16_t* Gb, bf16_t* Ob, int seq, char* lds,
;                                           const float* qgain, const float* cosA, const float* sinA, int t0) {
;     ...
;         u32x4 wx = {cvtpk(xo[0], xo[1]), cvtpk(xo[2], xo[3]), cvtpk(xo[4], xo[5]), cvtpk(xo[6], xo[7])}, wy = {cvtpk(yo[0], yo[1]), cvtpk(yo[2], yo[3]), cvtpk(yo[4], yo[5]), cvtpk(yo[6], yo[7])};
;         qr[dx] = *reinterpret_cast<bf16x8*>(&wx); qr[dy] = *reinterpret_cast<bf16x8*>(&wy); } }
;   }
;   const int sr = tid >> 4, sc = (tid & 15) * 8, vst0 = v_st(sr, sc), vst1 = v_st(32 + sr, sc);
;   const int vb0 = (int)(uintptr_t)V_lds + v_rd_base(lane);
;   struct { bf16x8 vs0, vs1, ks0, ks1; } sr_[2];
;     ...
;   f32x16 pA0, pA1, pB0, pB1; float mnA, mnB, alA, alB; bf16x8 pa0, pa1, pa2, pa3; const int NT = seq / KVBLK;
;   constexpr int SE = 0, SO = 1;
;   SLOAD(SE, 0); asm volatile("s_waitcnt vmcnt(0)" ::: "memory"); SWRITE(0, SE); __syncthreads();
;   qkt(pA0, pA1, K_lds, qr, r32, hi); partialSM(pA0, pA1, m_reg, mnA, alA);
	v_mov_b32_e32 v3, v54
	v_pk_mul_f32 v[2:3], v[2:3], v[0:1]
	v_mov_b32_e32 v26, v23
	v_sub_f32_e32 v13, v2, v3
	v_mov_b32_e32 v2, v54
	v_mov_b32_e32 v3, v50
	v_pk_mul_f32 v[0:1], v[2:3], v[0:1]
	v_mov_b32_e32 v54, v51
	v_add_f32_e32 v14, v0, v1
	v_pk_mul_f32 v[0:1], v[8:9], v[36:37] op_sel_hi:[0,1]
	v_pk_mul_f32 v[0:1], v[0:1], v[26:27]
	v_mov_b32_e32 v50, v55
	v_pk_mul_f32 v[2:3], v[54:55], v[0:1]
	v_pk_mul_f32 v[0:1], v[50:51], v[0:1]
	v_sub_f32_e32 v15, v2, v3
	v_add_f32_e32 v16, v0, v1
	v_pk_mul_f32 v[0:1], v[8:9], v[34:35] op_sel_hi:[0,1]
	v_mov_b32_e32 v2, v24
	v_mov_b32_e32 v3, v28
	v_pk_mul_f32 v[0:1], v[0:1], v[2:3]
	v_mov_b32_e32 v2, v52
	v_mov_b32_e32 v3, v56
	v_pk_mul_f32 v[2:3], v[2:3], v[0:1]
	v_mov_b32_e32 v28, v25
	v_sub_f32_e32 v17, v2, v3
	v_mov_b32_e32 v2, v56
	v_mov_b32_e32 v3, v52
	v_pk_mul_f32 v[0:1], v[2:3], v[0:1]
	v_mov_b32_e32 v56, v53
	v_add_f32_e32 v18, v0, v1
	v_pk_mul_f32 v[0:1], v[8:9], v[32:33] op_sel_hi:[0,1]
	v_pk_mul_f32 v[0:1], v[0:1], v[28:29]
	v_mov_b32_e32 v52, v57
	v_pk_mul_f32 v[2:3], v[56:57], v[0:1]
	v_pk_mul_f32 v[0:1], v[52:53], v[0:1]
	v_sub_f32_e32 v2, v2, v3
	v_add_f32_e32 v0, v0, v1
	v_cvt_pk_bf16_f32 v124, v9, v7
	v_cvt_pk_bf16_f32 v125, v4, v5
	v_cvt_pk_bf16_f32 v126, v13, v15
	v_cvt_pk_bf16_f32 v127, v17, v2
	v_cvt_pk_bf16_f32 v120, v6, v10
	v_cvt_pk_bf16_f32 v121, v11, v12
	v_cvt_pk_bf16_f32 v122, v14, v16
	v_lshlrev_b32_e32 v16, 3, v94
	v_cvt_pk_bf16_f32 v123, v18, v0
	v_and_b32_e32 v180, 0x78, v16
	v_mad_i64_i32 v[0:1], s[22:23], v48, s69, 0
	v_or_b32_e32 v0, v0, v180
	v_add_u32_e32 v17, 32, v48
	v_lshlrev_b64 v[8:9], 1, v[0:1]
	v_lshl_add_u64 v[0:1], s[42:43], 0, v[8:9]
	v_mad_i64_i32 v[4:5], s[22:23], v17, s69, 0
	global_load_dwordx4 v[0:3], v[0:1], off
	v_or_b32_e32 v4, v4, v180
	v_lshlrev_b64 v[12:13], 1, v[4:5]
	v_lshl_add_u64 v[4:5], s[42:43], 0, v[12:13]
	v_lshl_add_u64 v[8:9], s[36:37], 0, v[8:9]
	global_load_dwordx4 v[4:7], v[4:5], off
	v_lshl_add_u64 v[12:13], s[36:37], 0, v[12:13]
	global_load_dwordx4 v[8:11], v[8:9], off
	v_and_b32_e32 v18, 0xfffff0, v48
	global_load_dwordx4 v[12:15], v[12:13], off
	v_lshlrev_b32_e32 v19, 1, v48
	v_and_or_b32 v18, v19, 8, v18
	v_lshrrev_b32_e32 v19, 1, v48
	v_lshrrev_b32_e32 v18, 1, v18
	v_bfe_u32 v16, v16, 5, 2
	v_and_b32_e32 v20, 3, v48
	v_or_b32_e32 v18, v18, v16
	v_and_or_b32 v19, v19, 4, v20
	v_lshlrev_b32_e32 v20, 1, v180
	v_and_b32_e32 v22, 0xfffff0, v17
	v_lshlrev_b32_e32 v23, 1, v17
	v_lshlrev_b32_e32 v18, 9, v18
	v_lshlrev_b32_e32 v19, 6, v19
	v_and_b32_e32 v21, 48, v20
	v_and_or_b32 v22, v23, 8, v22
	v_or3_b32 v18, v18, v19, v21
	v_lshrrev_b32_e32 v22, 1, v22
	v_or_b32_e32 v16, v22, v16
	v_add_u32_e32 v192, 0, v18
	v_lshlrev_b32_e32 v16, 9, v16
	s_waitcnt vmcnt(0)
	v_or3_b32 v16, v16, v19, v21
	v_add_u32_e32 v193, 0, v16
	v_or_b32_e32 v66, v66, v180
	v_lshlrev_b64 v[66:67], 1, v[66:67]
	v_or_b32_e32 v70, v70, v180
	v_lshl_add_u64 v[68:69], s[42:43], 0, v[66:67]
	v_lshlrev_b64 v[70:71], 1, v[70:71]
	v_lshl_add_u64 v[66:67], s[36:37], 0, v[66:67]
	v_lshl_add_u64 v[72:73], s[42:43], 0, v[70:71]
	s_waitcnt vmcnt(3)
	ds_write_b128 v192, v[0:3]
	v_lshlrev_b32_e32 v0, 8, v48
	v_and_b32_e32 v1, 0x70, v94
	v_bitop3_b32 v0, v20, v0, v1 bitop3:0xde
	v_add_u32_e32 v199, 0, v0
	v_lshlrev_b32_e32 v0, 8, v17
	s_waitcnt vmcnt(2)
	ds_write_b128 v193, v[4:7]
	s_waitcnt vmcnt(1)
	ds_write_b128 v199, v[8:11] offset:32768
	v_bitop3_b32 v0, v20, v0, v1 bitop3:0xde
	v_lshlrev_b32_e32 v8, 8, v181
	v_and_b32_e32 v9, 0x70, v185
	v_add_u32_e32 v200, 0, v0
	v_bitop3_b32 v0, v176, v8, v9 bitop3:0xde
	v_add_u32_e32 v201, 0, v0
	s_waitcnt vmcnt(0)
	ds_write_b128 v200, v[12:15] offset:32768
	s_waitcnt lgkmcnt(0)
	s_barrier
	ds_read_b128 v[0:3], v201 offset:32768
	ds_read_b128 v[4:7], v201 offset:40960
	s_waitcnt lgkmcnt(1)
	v_mfma_f32_32x32x16_bf16 v[32:47], v[0:3], v[100:103], 0
	v_or_b32_e32 v0, 32, v176
	v_bitop3_b32 v0, v0, v8, v9 bitop3:0xde
	v_add_u32_e32 v204, 0, v0
	v_lshlrev_b32_e32 v10, 3, v186
	s_waitcnt lgkmcnt(0)
	v_mfma_f32_32x32x16_bf16 v[16:31], v[4:7], v[100:103], 0
	ds_read_b128 v[0:3], v204 offset:32768
	ds_read_b128 v[4:7], v204 offset:40960
	s_waitcnt lgkmcnt(1)
	v_mfma_f32_32x32x16_bf16 v[32:47], v[0:3], v[108:111], v[32:47]
	v_or_b32_e32 v0, 64, v176
	v_bitop3_b32 v0, v0, v8, v9 bitop3:0xde
	v_add_u32_e32 v205, 0, v0
	s_waitcnt lgkmcnt(0)
	v_mfma_f32_32x32x16_bf16 v[16:31], v[4:7], v[108:111], v[16:31]
	ds_read_b128 v[0:3], v205 offset:32768
	ds_read_b128 v[4:7], v205 offset:40960
	s_waitcnt lgkmcnt(1)
	v_mfma_f32_32x32x16_bf16 v[32:47], v[0:3], v[96:99], v[32:47]
	v_or_b32_e32 v0, 0x60, v176
	v_bitop3_b32 v0, v0, v8, v9 bitop3:0xde
	v_add_u32_e32 v202, 0, v0
	s_waitcnt lgkmcnt(0)
	v_mfma_f32_32x32x16_bf16 v[16:31], v[4:7], v[96:99], v[16:31]
	ds_read_b128 v[0:3], v202 offset:32768
	ds_read_b128 v[4:7], v202 offset:40960
	s_waitcnt lgkmcnt(1)
	v_mfma_f32_32x32x16_bf16 v[32:47], v[0:3], v[104:107], v[32:47]
	v_or_b32_e32 v0, 0x80, v176
	v_bitop3_b32 v0, v0, v8, v9 bitop3:0xde
	v_add_u32_e32 v203, 0, v0
	s_waitcnt lgkmcnt(0)
	v_mfma_f32_32x32x16_bf16 v[16:31], v[4:7], v[104:107], v[16:31]
	ds_read_b128 v[0:3], v203 offset:32768
	ds_read_b128 v[4:7], v203 offset:40960
	s_waitcnt lgkmcnt(1)
	v_mfma_f32_32x32x16_bf16 v[32:47], v[0:3], v[116:119], v[32:47]
	v_or_b32_e32 v0, 0xa0, v176
	v_bitop3_b32 v0, v0, v8, v9 bitop3:0xde
	v_add_u32_e32 v206, 0, v0
	ds_read_b128 v[0:3], v206 offset:32768
	s_waitcnt lgkmcnt(1)
	v_mfma_f32_32x32x16_bf16 v[16:31], v[4:7], v[116:119], v[16:31]
	v_and_b32_e32 v4, 0x3fffffc0, v94
	v_lshl_add_u32 v187, v4, 2, s19
	v_and_b32_e32 v4, 0xc0, v185
	v_and_or_b32 v11, v10, 24, v4
	ds_read_b128 v[4:7], v206 offset:40960
	v_and_b32_e32 v10, 0x100, v10
	s_mov_b32 s19, -1
	s_waitcnt lgkmcnt(1)
; #define SLOAD(i, k0) do { sr_[i].vs0 = ld8(&Vh[(long)((k0) + sr) * LDK + sc]); sr_[i].vs1 = ld8(&Vh[(long)((k0) + 32 + sr) * LDK + sc]); \
;     sr_[i].ks0 = ld8(&Kh[(long)((k0) + sr) * LDK + sc]); sr_[i].ks1 = ld8(&Kh[(long)((k0) + 32 + sr) * LDK + sc]); } while (0)
; #define SWRITE(b, i) do { *(bf16x8*)(V_lds + (b) * SHM_V + vst0) = sr_[i].vs0;          \
;     *(bf16x8*)(V_lds + (b) * SHM_V + vst1) = sr_[i].vs1; int kc = sc * 2;               \
;     *(bf16x8*)(K_lds + (b) * SHM_K + KSWZ(sr, kc)) = sr_[i].ks0;                       \
;     *(bf16x8*)(K_lds + (b) * SHM_K + KSWZ(32 + sr, kc)) = sr_[i].ks1; } while (0)
; #define SWAIT() asm volatile("s_waitcnt vmcnt(4)" ::: "memory")
; __device__ __forceinline__ void partialSM(f32x16& p0, f32x16& p1, float& m_reg, float& mn, float& alpha) {
;   constexpr float C = SCALE * 1.4426950408889634f;
;   float pmax = p0[0]; for (int r = 1; r < 16; ++r) pmax = fmaxf(pmax, p0[r]); for (int r = 0; r < 16; ++r) pmax = fmaxf(pmax, p1[r]);
;   { auto rr = __builtin_amdgcn_permlane32_swap(__float_as_uint(pmax), __float_as_uint(pmax), false, false);
;     pmax = fmaxf(__uint_as_float(rr[0]), __uint_as_float(rr[1])); }
;   if (__builtin_expect(__all(pmax - m_reg <= THR / SCALE), 1)) { mn = m_reg; alpha = 1.f; }
;   else { mn = fmaxf(m_reg, pmax); alpha = __builtin_amdgcn_exp2f((m_reg - mn) * C); m_reg = mn; }
;   float mnC = -mn * C;
;   for (int r = 0; r < 16; ++r) p0[r] = fmaf(p0[r], C, mnC); for (int r = 0; r < 16; ++r) p1[r] = fmaf(p1[r], C, mnC);
;   for (int r = 0; r < 16; ++r) p0[r] = __builtin_amdgcn_exp2f(p0[r]);
; __device__ __forceinline__ void attn_body(const bf16_t* Qb, const bf16_t* Kh, const bf16_t* Vh, const bf16_t* Gb, bf16_t* Ob, int seq, char* lds,
;                                           const float* qgain, const float* cosA, const float* sinA, int t0) {
;     ...
;   SLOAD(SE, 0); asm volatile("s_waitcnt vmcnt(0)" ::: "memory"); SWRITE(0, SE); __syncthreads();
;   qkt(pA0, pA1, K_lds, qr, r32, hi); partialSM(pA0, pA1, m_reg, mnA, alA);
;   SLOAD(SO, KVBLK); if (2 < NT) SLOAD(SE, 2 * KVBLK);
;   SWAIT(); SWRITE(1, SO); __syncthreads();
	v_mfma_f32_32x32x16_bf16 v[32:47], v[0:3], v[124:127], v[32:47]
	v_lshlrev_b32_e32 v0, 1, v94
	v_and_b32_e32 v12, 32, v0
	v_or_b32_e32 v0, 0xc0, v176
	v_bitop3_b32 v0, v0, v8, v9 bitop3:0xde
	v_add_u32_e32 v207, 0, v0
	ds_read_b128 v[0:3], v207 offset:32768
	v_or3_b32 v74, v11, v12, v10
	s_waitcnt lgkmcnt(1)
	v_mfma_f32_32x32x16_bf16 v[16:31], v[4:7], v[124:127], v[16:31]
	ds_read_b128 v[4:7], v207 offset:40960
	v_add_u32_e32 v191, s21, v74
	v_lshl_add_u32 v188, v181, 2, v187
	s_waitcnt lgkmcnt(1)
	v_mfma_f32_32x32x16_bf16 v[32:47], v[0:3], v[112:115], v[32:47]
	v_or_b32_e32 v0, 0xe0, v176
	v_bitop3_b32 v0, v0, v8, v9 bitop3:0xde
	v_add_u32_e32 v208, 0, v0
	ds_read_b128 v[0:3], v208 offset:32768
	ds_read_b128 v[50:53], v208 offset:40960
	s_waitcnt lgkmcnt(2)
	v_mfma_f32_32x32x16_bf16 v[16:31], v[4:7], v[112:115], v[16:31]
	s_waitcnt lgkmcnt(1)
	v_mfma_f32_32x32x16_bf16 v[32:47], v[0:3], v[120:123], v[32:47]
	v_mov_b64_e32 v[0:1], s[72:73]
	v_mov_b64_e32 v[2:3], s[74:75]
	v_mov_b64_e32 v[4:5], s[76:77]
	v_mov_b64_e32 v[6:7], s[78:79]
	v_mov_b64_e32 v[8:9], s[80:81]
	v_mov_b64_e32 v[10:11], s[82:83]
	v_mov_b64_e32 v[12:13], s[84:85]
	s_waitcnt lgkmcnt(0)
	v_mfma_f32_32x32x16_bf16 v[16:31], v[50:53], v[120:123], v[16:31]
	s_nop 2
	v_max_f32_e32 v50, v33, v33
	v_max_f32_e32 v51, v32, v32
	v_max_f32_e32 v50, v51, v50
	v_max3_f32 v50, v50, v34, v35
	v_max3_f32 v50, v50, v36, v37
	v_max3_f32 v50, v50, v38, v39
	v_max3_f32 v50, v50, v40, v41
	v_max3_f32 v50, v50, v42, v43
	v_max3_f32 v50, v50, v44, v45
	v_max3_f32 v50, v50, v46, v47
	v_max3_f32 v50, v50, v16, v17
	v_max3_f32 v50, v50, v18, v19
	v_max3_f32 v50, v50, v20, v21
	v_max3_f32 v50, v50, v22, v23
	v_max3_f32 v50, v50, v24, v25
	v_max3_f32 v50, v50, v26, v27
	v_max3_f32 v50, v50, v28, v29
	v_max3_f32 v75, v50, v30, v31
	v_add_u32_e32 v50, 64, v48
	v_add_u32_e32 v52, 0x60, v48
	v_mad_i64_i32 v[50:51], s[22:23], v50, s69, 0
	v_mad_i64_i32 v[52:53], s[22:23], v52, s69, 0
	v_or_b32_e32 v50, v50, v180
	v_or_b32_e32 v52, v52, v180
	v_lshlrev_b64 v[58:59], 1, v[50:51]
	v_lshlrev_b64 v[60:61], 1, v[52:53]
	v_lshl_add_u64 v[50:51], s[42:43], 0, v[58:59]
	v_lshl_add_u64 v[54:55], s[42:43], 0, v[60:61]
	v_lshl_add_u64 v[58:59], s[36:37], 0, v[58:59]
	v_lshl_add_u64 v[62:63], s[36:37], 0, v[60:61]
	global_load_dwordx4 v[50:53], v[50:51], off
	s_nop 0
	global_load_dwordx4 v[54:57], v[54:55], off
	s_nop 0
	global_load_dwordx4 v[58:61], v[58:59], off
	s_nop 0
	global_load_dwordx4 v[62:65], v[62:63], off
	s_nop 0
	global_load_dwordx4 v[128:131], v[68:69], off
	global_load_dwordx4 v[132:135], v[72:73], off
	v_lshl_add_u64 v[68:69], s[36:37], 0, v[70:71]
	global_load_dwordx4 v[240:243], v[66:67], off
	global_load_dwordx4 v[246:249], v[68:69], off
	v_add_co_u32_e32 v66, vcc, 0xa0000, v66
	s_nop 1
	v_addc_co_u32_e32 v67, vcc, 0, v67, vcc
	v_add_co_u32_e32 v68, vcc, 0xa0000, v68
	s_nop 1
	v_addc_co_u32_e32 v69, vcc, 0, v69, vcc
	global_load_dwordx4 v[136:139], v[66:67], off
	global_load_dwordx4 v[140:143], v[68:69], off
	v_mov_b32_e32 v76, v75
	s_nop 1
	v_permlane32_swap_b32_e32 v75, v76
	v_max_f32_e32 v66, v76, v76
	v_max_f32_e32 v67, v75, v75
	v_max_f32_e32 v66, v67, v66
	v_add_f32_e32 v67, 0x7149f2ca, v66
	v_max_f32_e32 v66, 0xf149f2ca, v66
	v_cmp_ge_f32_e32 vcc, s71, v67
	v_sub_f32_e32 v67, 0xf149f2ca, v66
	v_mul_f32_e32 v67, 0x3e0293ee, v67
	v_exp_f32_e32 v67, v67
	s_cmp_eq_u64 vcc, exec
	s_cselect_b64 vcc, -1, 0
	v_mov_b32_e32 v68, 0xf149f2ca
	v_cndmask_b32_e32 v164, v66, v68, vcc
	v_mul_f32_e32 v66, 0xbe0293ee, v164
	v_cndmask_b32_e64 v209, v67, 1.0, vcc
	v_mov_b32_e32 v67, v66
	v_fmac_f32_e32 v67, 0x3e0293ee, v47
	v_mov_b64_e32 v[14:15], s[86:87]
	s_movk_i32 s72, 0x2800
	v_pk_fma_f32 v[156:157], v[16:17], s[62:63], v[66:67] op_sel_hi:[1,0,0]
	v_lshl_add_u64 v[16:17], v[48:49], 0, s[38:39]
	v_fmamk_f32 v32, v32, 0x3e0293ee, v66
	v_fmamk_f32 v33, v33, 0x3e0293ee, v66
	v_fmamk_f32 v34, v34, 0x3e0293ee, v66
	v_fmamk_f32 v35, v35, 0x3e0293ee, v66
	v_fmamk_f32 v36, v36, 0x3e0293ee, v66
	v_fmamk_f32 v37, v37, 0x3e0293ee, v66
	v_fmamk_f32 v38, v38, 0x3e0293ee, v66
	v_fmamk_f32 v39, v39, 0x3e0293ee, v66
	v_fmamk_f32 v40, v40, 0x3e0293ee, v66
	v_fmamk_f32 v41, v41, 0x3e0293ee, v66
	v_fmamk_f32 v42, v42, 0x3e0293ee, v66
	v_fmamk_f32 v43, v43, 0x3e0293ee, v66
	v_fmamk_f32 v44, v44, 0x3e0293ee, v66
	v_fmamk_f32 v45, v45, 0x3e0293ee, v66
	v_fmamk_f32 v46, v46, 0x3e0293ee, v66
	v_pk_fma_f32 v[154:155], v[18:19], s[62:63], v[66:67] op_sel_hi:[1,0,0]
	v_mad_u64_u32 v[18:19], s[22:23], v16, s72, 0
	v_and_b32_e32 v16, 15, v94
	v_exp_f32_e32 v175, v32
	v_exp_f32_e32 v216, v33
	v_exp_f32_e32 v161, v34
	v_exp_f32_e32 v213, v35
	v_exp_f32_e32 v162, v36
	v_exp_f32_e32 v174, v37
	v_exp_f32_e32 v163, v38
	v_exp_f32_e32 v173, v39
	v_exp_f32_e32 v170, v40
	v_exp_f32_e32 v172, v41
	v_exp_f32_e32 v169, v42
	v_exp_f32_e32 v171, v43
	v_exp_f32_e32 v166, v44
	v_exp_f32_e32 v168, v45
	v_exp_f32_e32 v165, v46
	v_exp_f32_e32 v167, v67
	v_lshlrev_b32_e32 v16, 4, v16
	s_waitcnt vmcnt(4)
	v_mad_i32_i24 v17, v17, s72, v19
	v_or3_b32 v16, v18, s20, v16
	v_pk_fma_f32 v[150:151], v[30:31], s[62:63], v[66:67] op_sel_hi:[1,0,0]
	v_pk_fma_f32 v[152:153], v[28:29], s[62:63], v[66:67] op_sel_hi:[1,0,0]
	v_pk_fma_f32 v[158:159], v[26:27], s[62:63], v[66:67] op_sel_hi:[1,0,0]
	v_pk_fma_f32 v[144:145], v[24:25], s[62:63], v[66:67] op_sel_hi:[1,0,0]
	v_pk_fma_f32 v[146:147], v[22:23], s[62:63], v[66:67] op_sel_hi:[1,0,0]
	v_pk_fma_f32 v[148:149], v[20:21], s[62:63], v[66:67] op_sel_hi:[1,0,0]
	s_waitcnt vmcnt(7)
	ds_write_b128 v192, v[50:53] offset:16384
	s_waitcnt vmcnt(6)
	ds_write_b128 v193, v[54:57] offset:16384
	s_waitcnt vmcnt(5)
	ds_write_b128 v199, v[58:61] offset:49152
	s_waitcnt vmcnt(4)
	ds_write_b128 v200, v[62:65] offset:49152
	s_addk_i32 s21, 0x4000
	v_lshl_add_u64 v[182:183], s[50:51], 0, v[16:17]
	v_mov_b64_e32 v[62:63], v[14:15]
	v_mov_b64_e32 v[46:47], v[14:15]
	v_mov_b64_e32 v[30:31], v[14:15]
	v_cmp_gt_u32_e64 s[36:37], 32, v186
	v_add_u32_e32 v190, s21, v74
	v_mov_b64_e32 v[60:61], v[12:13]
	v_mov_b64_e32 v[58:59], v[10:11]
	v_mov_b64_e32 v[56:57], v[8:9]
	v_mov_b64_e32 v[54:55], v[6:7]
	v_mov_b64_e32 v[52:53], v[4:5]
	v_mov_b64_e32 v[50:51], v[2:3]
	v_mov_b64_e32 v[48:49], v[0:1]
	v_mov_b64_e32 v[44:45], v[12:13]
	v_mov_b64_e32 v[42:43], v[10:11]
	v_mov_b64_e32 v[40:41], v[8:9]
	v_mov_b64_e32 v[38:39], v[6:7]
	v_mov_b64_e32 v[36:37], v[4:5]
	v_mov_b64_e32 v[34:35], v[2:3]
	v_mov_b64_e32 v[32:33], v[0:1]
	v_mov_b64_e32 v[28:29], v[12:13]
	v_mov_b64_e32 v[26:27], v[10:11]
	v_mov_b64_e32 v[24:25], v[8:9]
	v_mov_b64_e32 v[22:23], v[6:7]
	v_mov_b64_e32 v[20:21], v[4:5]
	v_mov_b64_e32 v[18:19], v[2:3]
	v_mov_b64_e32 v[16:17], v[0:1]
	s_waitcnt lgkmcnt(0)
	s_barrier
	s_waitcnt vmcnt(2)
	ds_write_b128 v199, v[240:243] offset:32768
	ds_write_b128 v200, v[246:249] offset:32768
	s_nop 0

;     __device__ bool next(int i, Unit& u) const { if (i >= 2) return false; const int x = c & 7, q = c >> 3; u.pm = 32 * i + 4 * x + (q >> 3); u.pn = q & 7; return true; }
;     __device__ __forceinline__ void init(f32x4 (&acc)[2][2][4][2], const Unit& u, int wr, int wc, int fr, int fq) const {
;         const int col0 = u.pn * BM + wc * 32 + 4 * fq;
; #pragma unroll
;         for (int ai = 0; ai < 2; ++ai)
; #pragma unroll
;             for (int m = 0; m < 4; ++m) { const size_t off = (size_t)(u.pm * BM + ai * HALF + wr * 64 + m * 16 + fr) * DM + col0;
; #pragma unroll
;                 for (int bj = 0; bj < 2; ++bj)
; #pragma unroll
;                     for (int n = 0; n < 2; ++n) acc[ai][bj][m][n] = *(const f32x4*)(xin + off + bj * HALF + n * 16) * alpha; }
;     }
; template <class Epi, int K, int lda, class Sched = StaticOrder, bool ALIGN_EPI = true>
; __device__ __forceinline__ void gemm_phase(LAS unsigned char* lds, const Gemm g, const Sched& S, const Epi& E) {
;     ...
;         const bool has_next = S.next(ui + 1, nxt);
;         const char* nA = has_next ? (const char*)g.A + (size_t)nxt.pm * tstepA : cA; const char* nB = has_next ? (const char*)g.Bt + (size_t)nxt.pn * tstepB : cB;
;         for (int t = 0; t < nt; t += 2) {
;             const bool last = (t == nt - 2);
;             const char* a1 = cA + (size_t)(t + 1) * kstep;
;             const char* a2 = last ? nA : cA + (size_t)(t + 2) * kstep; const char* b2 = last ? nB : cB + (size_t)(t + 2) * kstep;
.LBB0_473:
	s_and_b64 s[20:21], s[44:45], exec
	s_cselect_b32 s20, s34, s34
	s_ashr_i32 s21, s20, 31
	s_lshl_b64 s[20:21], s[20:21], 20
	s_mov_b64 s[38:39], s[46:47]
	s_add_u32 s46, s8, s20
	s_addc_u32 s47, s9, s21
	s_and_b64 s[20:21], s[44:45], exec
	s_cselect_b32 s19, s47, s39
	s_cselect_b32 s20, s46, s38
	s_add_u32 s38, s38, 0x80080
	v_mov_b32_e32 v199, 0x358637bd
	s_waitcnt vmcnt(0)
	v_pk_mul_f32 v[2:3], v[2:3], s[68:69] op_sel_hi:[1,0]
	v_pk_mul_f32 v[0:1], v[0:1], s[68:69] op_sel_hi:[1,0]
	v_pk_mul_f32 v[6:7], v[6:7], s[68:69] op_sel_hi:[1,0]
	v_pk_mul_f32 v[4:5], v[4:5], s[68:69] op_sel_hi:[1,0]
	v_pk_mul_f32 v[10:11], v[10:11], s[68:69] op_sel_hi:[1,0]
	v_pk_mul_f32 v[8:9], v[8:9], s[68:69] op_sel_hi:[1,0]
	v_pk_mul_f32 v[14:15], v[14:15], s[68:69] op_sel_hi:[1,0]
	v_pk_mul_f32 v[12:13], v[12:13], s[68:69] op_sel_hi:[1,0]
	v_pk_mul_f32 v[18:19], v[18:19], s[68:69] op_sel_hi:[1,0]
	v_pk_mul_f32 v[16:17], v[16:17], s[68:69] op_sel_hi:[1,0]
	v_pk_mul_f32 v[22:23], v[22:23], s[68:69] op_sel_hi:[1,0]
	v_pk_mul_f32 v[20:21], v[20:21], s[68:69] op_sel_hi:[1,0]
	v_pk_mul_f32 v[26:27], v[26:27], s[68:69] op_sel_hi:[1,0]
	v_pk_mul_f32 v[24:25], v[24:25], s[68:69] op_sel_hi:[1,0]
	v_pk_mul_f32 v[30:31], v[30:31], s[68:69] op_sel_hi:[1,0]
	v_pk_mul_f32 v[28:29], v[28:29], s[68:69] op_sel_hi:[1,0]
	v_pk_mul_f32 v[34:35], v[34:35], s[68:69] op_sel_hi:[1,0]
	v_pk_mul_f32 v[32:33], v[32:33], s[68:69] op_sel_hi:[1,0]
	v_pk_mul_f32 v[38:39], v[38:39], s[68:69] op_sel_hi:[1,0]
	v_pk_mul_f32 v[36:37], v[36:37], s[68:69] op_sel_hi:[1,0]
	v_pk_mul_f32 v[42:43], v[42:43], s[68:69] op_sel_hi:[1,0]
	v_pk_mul_f32 v[40:41], v[40:41], s[68:69] op_sel_hi:[1,0]
	v_pk_mul_f32 v[46:47], v[46:47], s[68:69] op_sel_hi:[1,0]
	v_pk_mul_f32 v[44:45], v[44:45], s[68:69] op_sel_hi:[1,0]
	v_pk_mul_f32 v[50:51], v[50:51], s[68:69] op_sel_hi:[1,0]
	v_pk_mul_f32 v[48:49], v[48:49], s[68:69] op_sel_hi:[1,0]
	v_pk_mul_f32 v[54:55], v[54:55], s[68:69] op_sel_hi:[1,0]
	v_pk_mul_f32 v[52:53], v[52:53], s[68:69] op_sel_hi:[1,0]
	v_pk_mul_f32 v[58:59], v[58:59], s[68:69] op_sel_hi:[1,0]
	v_pk_mul_f32 v[56:57], v[56:57], s[68:69] op_sel_hi:[1,0]
	v_pk_mul_f32 v[62:63], v[62:63], s[68:69] op_sel_hi:[1,0]
	v_pk_mul_f32 v[60:61], v[60:61], s[68:69] op_sel_hi:[1,0]
	v_pk_mul_f32 v[66:67], v[66:67], s[68:69] op_sel_hi:[1,0]
	v_pk_mul_f32 v[64:65], v[64:65], s[68:69] op_sel_hi:[1,0]
	v_pk_mul_f32 v[70:71], v[70:71], s[68:69] op_sel_hi:[1,0]
	v_pk_mul_f32 v[68:69], v[68:69], s[68:69] op_sel_hi:[1,0]
	v_pk_mul_f32 v[74:75], v[74:75], s[68:69] op_sel_hi:[1,0]
	v_pk_mul_f32 v[72:73], v[72:73], s[68:69] op_sel_hi:[1,0]
	v_pk_mul_f32 v[78:79], v[78:79], s[68:69] op_sel_hi:[1,0]
	v_pk_mul_f32 v[76:77], v[76:77], s[68:69] op_sel_hi:[1,0]
	v_pk_mul_f32 v[82:83], v[82:83], s[68:69] op_sel_hi:[1,0]
	v_pk_mul_f32 v[80:81], v[80:81], s[68:69] op_sel_hi:[1,0]
	v_pk_mul_f32 v[86:87], v[86:87], s[68:69] op_sel_hi:[1,0]
	v_pk_mul_f32 v[84:85], v[84:85], s[68:69] op_sel_hi:[1,0]
	v_pk_mul_f32 v[90:91], v[90:91], s[68:69] op_sel_hi:[1,0]
	v_pk_mul_f32 v[88:89], v[88:89], s[68:69] op_sel_hi:[1,0]
	v_pk_mul_f32 v[94:95], v[94:95], s[68:69] op_sel_hi:[1,0]
	v_pk_mul_f32 v[92:93], v[92:93], s[68:69] op_sel_hi:[1,0]
	v_pk_mul_f32 v[98:99], v[98:99], s[68:69] op_sel_hi:[1,0]
	v_pk_mul_f32 v[96:97], v[96:97], s[68:69] op_sel_hi:[1,0]
	v_pk_mul_f32 v[102:103], v[102:103], s[68:69] op_sel_hi:[1,0]
	v_pk_mul_f32 v[100:101], v[100:101], s[68:69] op_sel_hi:[1,0]
	v_pk_mul_f32 v[106:107], v[106:107], s[68:69] op_sel_hi:[1,0]
	v_pk_mul_f32 v[104:105], v[104:105], s[68:69] op_sel_hi:[1,0]
	v_pk_mul_f32 v[110:111], v[110:111], s[68:69] op_sel_hi:[1,0]
	v_pk_mul_f32 v[108:109], v[108:109], s[68:69] op_sel_hi:[1,0]
	v_pk_mul_f32 v[114:115], v[114:115], s[68:69] op_sel_hi:[1,0]
	v_pk_mul_f32 v[112:113], v[112:113], s[68:69] op_sel_hi:[1,0]
	v_pk_mul_f32 v[118:119], v[118:119], s[68:69] op_sel_hi:[1,0]
	v_pk_mul_f32 v[116:117], v[116:117], s[68:69] op_sel_hi:[1,0]
	v_pk_mul_f32 v[122:123], v[122:123], s[68:69] op_sel_hi:[1,0]
	v_pk_mul_f32 v[120:121], v[120:121], s[68:69] op_sel_hi:[1,0]
	v_pk_mul_f32 v[126:127], v[126:127], s[68:69] op_sel_hi:[1,0]
	v_pk_mul_f32 v[124:125], v[124:125], s[68:69] op_sel_hi:[1,0]
	s_addc_u32 s39, s39, 0
	s_mov_b32 s21, -2
	s_mov_b64 s[74:75], s[50:51]
	s_nop 0
